# v33: v31 + latent attention items cache the layer-invariant SHIFT test per wave per layer (fast path skips two loads, a drain wait and two 6-step wave-max butterflies per item)
# speedup vs baseline: 1.0068x; 1.0008x over previous
.LBB0_479:
	s_or_b64 exec, exec, s[10:11]
	v_mov_b32_e32 v235, 0
	s_mov_b32 s100, 0
	s_nop 0
	v_writelane_b32 v255, s100, 43
	v_readlane_b32 s14, v255, 14
	s_cmp_lg_u32 s14, 3
	s_cselect_b64 s[10:11], -1, 0
	v_readlane_b32 s15, v255, 15
	v_writelane_b32 v255, s10, 18
	v_cvt_f32_u32_e32 v1, s14
	v_mul_f32_e32 v1, 0xbe99999a, v1
	v_writelane_b32 v255, s11, 19
	s_lshl_b32 s10, s14, 6
	s_mov_b32 s6, s10
	s_mov_b32 s11, s31
	v_writelane_b32 v255, s6, 20
	s_lshl_b64 s[10:11], s[10:11], 2
	v_mul_f32_e32 v2, 0x3fb8aa3b, v1
	v_writelane_b32 v255, s7, 21
	v_readlane_b32 s6, v254, 21
	s_add_u32 s10, s6, s10
	v_readlane_b32 s6, v254, 22
	s_addc_u32 s11, s6, s11
	v_writelane_b32 v255, s10, 22
	s_cmp_eq_u32 s14, 3
	s_cselect_b32 s6, 0, 16
	v_writelane_b32 v255, s11, 23
	s_mov_b64 s[10:11], s[0:1]
	s_cselect_b32 s10, 0, 64
	s_or_b32 s11, s6, 64
	v_writelane_b32 v255, s11, 24
	s_add_i32 s11, s11, s10
	v_writelane_b32 v255, s11, 25
	s_addk_i32 s11, 0x280
	v_writelane_b32 v255, s11, 26
	s_add_i32 s11, s11, s6
	v_writelane_b32 v255, s11, 27
	s_add_i32 s11, s11, s6
	v_writelane_b32 v255, s11, 28
	s_add_i32 s11, s11, s6
	s_add_i32 s18, s11, 0x180
	v_writelane_b32 v255, s18, 29
	s_add_i32 s18, s11, 0x280
	v_writelane_b32 v255, s18, 30
	v_writelane_b32 v255, s11, 31
	s_add_i32 s34, s11, 0x380
	s_mov_b32 s11, 0x3fb8aa3b
	v_fma_f32 v3, v1, s11, -v2
	v_rndne_f32_e32 v4, v2
	v_fmac_f32_e32 v3, 0x32a5705f, v1
	v_sub_f32_e32 v2, v2, v4
	v_add_f32_e32 v2, v2, v3
	v_exp_f32_e32 v2, v2
	v_cvt_i32_f32_e32 v3, v4
	s_lshl_b64 s[26:27], s[14:15], 12
	v_writelane_b32 v255, s26, 32
	s_mov_b32 s11, 0xc2ce8ed0
	v_ldexp_f32 v2, v2, v3
	v_writelane_b32 v255, s27, 33
	s_mul_i32 s26, s14, 0x3c00
	s_mov_b32 s27, s31
	v_writelane_b32 v255, s26, 34
	v_cmp_ngt_f32_e32 vcc, s11, v1
	s_mov_b32 s11, 0x42b17218
	v_writelane_b32 v255, s27, 35
	v_cndmask_b32_e32 v2, 0, v2, vcc
	v_cmp_nlt_f32_e32 vcc, s11, v1
	s_lshl_b32 s14, s14, 7
	s_mov_b32 s15, s31
	s_lshl_b32 s10, s10, 2
	s_lshl_b32 s6, s6, 4
	v_cndmask_b32_e32 v1, v220, v2, vcc
	v_mov_b32_e32 v2, 0x3f4ccccd
	v_writelane_b32 v255, s14, 36
	s_add_i32 s10, s10, s6
	v_fmamk_f32 v236, v1, 0xbf19999a, v2
	v_writelane_b32 v255, s15, 37
	s_xor_b32 s6, s10, 0xffffeb01
	v_sub_f32_e32 v227, 1.0, v236
	v_writelane_b32 v255, s6, 38
	s_branch .LBB0_484

.LBB0_742:
	s_andn2_b64 vcc, exec, s[10:11]
	s_cbranch_vccnz .LBB0_752
	v_readlane_b32 s100, v255, 43
	s_nop 0
	s_cmp_eq_u32 s100, 0
	s_cbranch_scc1 .Lattn_par_slow
	s_lshl_b32 s6, s26, 7
	v_xor_b32_e32 v1, 32, v223
	v_cmp_lt_i32_e32 vcc, v1, v225
	s_and_b32 s37, s6, 0xf80
	s_bfe_u32 s36, s26, 0x30005
	v_cndmask_b32_e32 v1, v223, v1, vcc
	v_lshlrev_b32_e32 v1, 2, v1
	v_cmp_lt_i32_e32 vcc, v243, v225
	s_ashr_i32 s27, s26, 8
	s_addk_i32 s37, 0x100
	v_cndmask_b32_e32 v5, v223, v243, vcc
	v_lshlrev_b32_e32 v176, 2, v5
	v_cmp_lt_i32_e32 vcc, v222, v225
	s_mov_b64 s[10:11], -1
	s_mul_i32 s48, s27, 0x1100
	v_cndmask_b32_e32 v5, v223, v222, vcc
	v_lshlrev_b32_e32 v175, 2, v5
	v_cmp_lt_i32_e32 vcc, v229, v225
	s_mul_hi_i32 s46, s27, 0x880000
	s_mul_i32 s47, s27, 0x880000
	v_cndmask_b32_e32 v5, v223, v229, vcc
	v_lshlrev_b32_e32 v174, 2, v5
	v_cmp_lt_i32_e32 vcc, v230, v225
	v_readlane_b32 s6, v255, 44
	s_nop 0
	v_cndmask_b32_e32 v5, v223, v230, vcc
	v_lshlrev_b32_e32 v173, 2, v5
	v_cmp_lt_i32_e32 vcc, v231, v225
	s_nop 1
	v_cndmask_b32_e32 v5, v223, v231, vcc
	v_lshlrev_b32_e32 v172, 2, v5
	s_bitcmp0_b32 s6, 0
	s_cbranch_scc0 .LBB0_747
	s_branch .Lattn_par_join
.Lattn_par_slow:
	v_mov_b32_e32 v1, v232
	s_load_dwordx4 s[40:43], s[44:45], 0x50
	v_readlane_b32 s10, v255, 20
	s_waitcnt vmcnt(0)
	v_mov_b32_e32 v3, v0
	s_lshl_b32 s6, s26, 7
	v_and_or_b32 v2, v1, 63, s10
	v_lshlrev_b64 v[2:3], 2, v[2:3]
	s_waitcnt lgkmcnt(0)
	v_lshl_add_u64 v[4:5], s[40:41], 0, v[2:3]
	global_load_dword v4, v[4:5], off
	v_lshl_add_u64 v[2:3], s[42:43], 0, v[2:3]
	global_load_dword v2, v[2:3], off
	v_xor_b32_e32 v1, 32, v223
	v_cmp_lt_i32_e32 vcc, v1, v225
	s_and_b32 s37, s6, 0xf80
	s_mov_b32 s6, 0x42800000
	v_cndmask_b32_e32 v1, v223, v1, vcc
	v_lshlrev_b32_e32 v1, 2, v1
	v_cmp_lt_i32_e32 vcc, v243, v225
	s_bfe_u32 s36, s26, 0x30005
	s_ashr_i32 s27, s26, 8
	s_addk_i32 s37, 0x100
	v_readlane_b32 s11, v255, 21
	s_mov_b64 s[10:11], -1
	s_mul_i32 s48, s27, 0x1100
	s_mul_hi_i32 s46, s27, 0x880000
	s_mul_i32 s47, s27, 0x880000
	s_waitcnt vmcnt(0)
	v_and_b32_e32 v5, 0x7fffffff, v4
	ds_bpermute_b32 v5, v1, v5
	v_max_f32_e64 v4, |v4|, |v4|
	v_and_b32_e32 v3, 0x7fffffff, v2
	ds_bpermute_b32 v3, v1, v3
	v_max_f32_e64 v2, |v2|, |v2|
	s_waitcnt lgkmcnt(1)
	v_max_f32_e32 v5, v5, v5
	v_max_f32_e32 v4, v4, v5
	v_cndmask_b32_e32 v5, v223, v243, vcc
	v_lshlrev_b32_e32 v176, 2, v5
	ds_bpermute_b32 v5, v176, v4
	s_waitcnt lgkmcnt(1)
	v_max_f32_e32 v3, v3, v3
	v_max_f32_e32 v2, v2, v3
	v_cmp_lt_i32_e32 vcc, v222, v225
	ds_bpermute_b32 v3, v176, v2
	s_waitcnt lgkmcnt(1)
	v_max_f32_e32 v5, v5, v5
	v_max_f32_e32 v4, v4, v5
	v_cndmask_b32_e32 v5, v223, v222, vcc
	v_lshlrev_b32_e32 v175, 2, v5
	ds_bpermute_b32 v5, v175, v4
	s_waitcnt lgkmcnt(1)
	v_max_f32_e32 v3, v3, v3
	v_max_f32_e32 v2, v2, v3
	ds_bpermute_b32 v3, v175, v2
	v_cmp_lt_i32_e32 vcc, v229, v225
	s_waitcnt lgkmcnt(1)
	v_max_f32_e32 v5, v5, v5
	v_max_f32_e32 v4, v4, v5
	v_cndmask_b32_e32 v5, v223, v229, vcc
	v_lshlrev_b32_e32 v174, 2, v5
	ds_bpermute_b32 v5, v174, v4
	s_waitcnt lgkmcnt(1)
	v_max_f32_e32 v3, v3, v3
	v_max_f32_e32 v2, v2, v3
	ds_bpermute_b32 v3, v174, v2
	v_cmp_lt_i32_e32 vcc, v230, v225
	s_waitcnt lgkmcnt(1)
	v_max_f32_e32 v5, v5, v5
	v_max_f32_e32 v4, v4, v5
	v_cndmask_b32_e32 v5, v223, v230, vcc
	v_lshlrev_b32_e32 v173, 2, v5
	ds_bpermute_b32 v5, v173, v4
	s_waitcnt lgkmcnt(1)
	v_max_f32_e32 v3, v3, v3
	v_max_f32_e32 v2, v2, v3
	ds_bpermute_b32 v3, v173, v2
	v_cmp_lt_i32_e32 vcc, v231, v225
	s_waitcnt lgkmcnt(1)
	v_max_f32_e32 v5, v5, v5
	v_max_f32_e32 v4, v4, v5
	v_cndmask_b32_e32 v5, v223, v231, vcc
	v_lshlrev_b32_e32 v172, 2, v5
	s_waitcnt lgkmcnt(0)
	v_max_f32_e32 v3, v3, v3
	ds_bpermute_b32 v5, v172, v4
	v_max_f32_e32 v2, v2, v3
	ds_bpermute_b32 v3, v172, v2
	s_waitcnt lgkmcnt(1)
	v_max_f32_e32 v5, v5, v5
	v_max_f32_e32 v4, v4, v5
	s_waitcnt lgkmcnt(0)
	v_max_f32_e32 v3, v3, v3
	v_mul_f32_e32 v4, 0x41000000, v4
	v_max_f32_e32 v2, v2, v3
	v_mul_f32_e32 v2, v4, v2
	v_mul_f32_e32 v2, 0x3fb8aa3b, v2
	v_cmp_gt_f32_e32 vcc, s6, v2
	s_nop 1
	v_cndmask_b32_e64 v2, 0, 1, vcc
	s_nop 0
	v_readfirstlane_b32 s6, v2
	s_nop 1
	v_writelane_b32 v255, s6, 44
	s_mov_b32 s100, 1
	s_nop 0
	v_writelane_b32 v255, s100, 43
	s_bitcmp0_b32 s6, 0
	s_cbranch_scc0 .LBB0_747
.Lattn_par_join:
	v_mov_b32_e32 v18, v232
	v_readlane_b32 s10, v255, 20
	v_and_b32_e32 v182, 63, v18
	v_mov_b32_e32 v3, v0
	v_or_b32_e32 v2, s10, v182
	v_lshlrev_b64 v[2:3], 2, v[2:3]
	v_lshl_add_u64 v[4:5], s[40:41], 0, v[2:3]
	global_load_dword v4, v[4:5], off
	s_load_dwordx8 s[52:59], s[44:45], 0x60
	s_add_i32 s6, s37, s48
	v_and_b32_e32 v178, 15, v18
	v_ashrrev_i32_e32 v181, 6, v18
	v_and_b32_e32 v179, 1, v181
	s_lshl_b32 s30, s36, 8
	v_lshlrev_b32_e32 v52, 7, v179
	v_mov_b32_e32 v53, v0
	v_and_b32_e32 v50, 48, v18
	v_mov_b32_e32 v51, v0
	v_readlane_b32 s11, v255, 21
	s_lshl_b32 s49, s36, 7
	s_mov_b64 s[10:11], 0x14610000
	v_ashrrev_i32_e32 v54, 4, v18
	v_ashrrev_i32_e32 v55, 31, v54
	v_lshlrev_b64 v[56:57], 11, v[54:55]
	v_bfe_u32 v177, v18, 4, 2
	v_lshlrev_b32_e32 v122, 4, v178
	v_mov_b32_e32 v123, v0
	s_movk_i32 s18, 0x2200
	v_and_b32_e32 v20, 0xfffffe3, v54
	s_mov_b32 s40, 0
	s_waitcnt vmcnt(0)
	v_and_b32_e32 v5, 0x7fffffff, v4
	ds_bpermute_b32 v5, v1, v5
	v_max_f32_e64 v4, |v4|, |v4|
	s_waitcnt lgkmcnt(0)
	v_max_f32_e32 v5, v5, v5
	v_max_f32_e32 v4, v4, v5
	ds_bpermute_b32 v5, v176, v4
	s_waitcnt lgkmcnt(0)
	v_max_f32_e32 v5, v5, v5
	v_max_f32_e32 v4, v4, v5
	ds_bpermute_b32 v5, v175, v4
	s_waitcnt lgkmcnt(0)
	v_max_f32_e32 v5, v5, v5
	v_max_f32_e32 v4, v4, v5
	ds_bpermute_b32 v5, v174, v4
	s_waitcnt lgkmcnt(0)
	v_max_f32_e32 v5, v5, v5
	v_max_f32_e32 v4, v4, v5
	ds_bpermute_b32 v5, v173, v4
	s_waitcnt lgkmcnt(0)
	v_max_f32_e32 v5, v5, v5
	v_max_f32_e32 v4, v4, v5
	ds_bpermute_b32 v5, v172, v4
	s_waitcnt lgkmcnt(0)
	v_max_f32_e32 v5, v5, v5
	v_max_f32_e32 v6, v4, v5
	v_lshl_add_u64 v[4:5], s[42:43], 0, v[2:3]
	global_load_dword v4, v[4:5], off
	s_load_dwordx2 s[42:43], s[44:45], 0xb0
	s_waitcnt vmcnt(0)
	v_and_b32_e32 v5, 0x7fffffff, v4
	ds_bpermute_b32 v5, v1, v5
	v_max_f32_e64 v4, |v4|, |v4|
	s_waitcnt lgkmcnt(0)
	v_max_f32_e32 v5, v5, v5
	v_max_f32_e32 v4, v4, v5
	ds_bpermute_b32 v5, v176, v4
	s_waitcnt lgkmcnt(0)
	v_max_f32_e32 v5, v5, v5
	v_max_f32_e32 v4, v4, v5
	ds_bpermute_b32 v5, v175, v4
	s_waitcnt lgkmcnt(0)
	v_max_f32_e32 v5, v5, v5
	v_max_f32_e32 v4, v4, v5
	ds_bpermute_b32 v5, v174, v4
	s_waitcnt lgkmcnt(0)
	v_max_f32_e32 v5, v5, v5
	v_max_f32_e32 v4, v4, v5
	ds_bpermute_b32 v5, v173, v4
	s_waitcnt lgkmcnt(0)
	v_max_f32_e32 v5, v5, v5
	v_max_f32_e32 v4, v4, v5
	ds_bpermute_b32 v5, v172, v4
	s_waitcnt lgkmcnt(0)
	v_max_f32_e32 v5, v5, v5
	v_max_f32_e32 v4, v4, v5
	v_mul_f32_e32 v5, 0x41000000, v6
	v_mul_f32_e32 v19, v5, v4
	v_lshl_add_u64 v[4:5], s[52:53], 0, v[2:3]
	global_load_dword v6, v[4:5], off
	v_lshl_add_u64 v[4:5], s[54:55], 0, v[2:3]
	global_load_dword v4, v[4:5], off
	v_mul_f32_e32 v171, 0x3fb8aa3b, v19
	s_waitcnt vmcnt(0)
	v_mul_f32_e32 v5, v6, v4
	ds_bpermute_b32 v5, v1, v5
	s_waitcnt lgkmcnt(0)
	v_fmac_f32_e32 v5, v6, v4
	ds_bpermute_b32 v4, v176, v5
	s_waitcnt lgkmcnt(0)
	v_add_f32_e32 v4, v5, v4
	ds_bpermute_b32 v5, v175, v4
	s_waitcnt lgkmcnt(0)
	v_add_f32_e32 v4, v4, v5
	ds_bpermute_b32 v5, v174, v4
	s_waitcnt lgkmcnt(0)
	v_add_f32_e32 v132, v4, v5
	v_lshl_add_u64 v[4:5], s[56:57], 0, v[2:3]
	v_lshl_add_u64 v[2:3], s[58:59], 0, v[2:3]
	global_load_dword v4, v[4:5], off
	ds_bpermute_b32 v133, v173, v132
	global_load_dword v2, v[2:3], off
	s_waitcnt vmcnt(0)
	v_mul_f32_e32 v3, v4, v2
	ds_bpermute_b32 v3, v1, v3
	s_waitcnt lgkmcnt(0)
	v_fmac_f32_e32 v3, v4, v2
	ds_bpermute_b32 v2, v176, v3
	s_waitcnt lgkmcnt(0)
	v_add_f32_e32 v2, v3, v2
	ds_bpermute_b32 v3, v175, v2
	s_waitcnt lgkmcnt(0)
	v_add_f32_e32 v2, v2, v3
	ds_bpermute_b32 v3, v174, v2
	s_waitcnt lgkmcnt(0)
	v_add_f32_e32 v134, v2, v3
	v_ashrrev_i32_e32 v2, 2, v18
	v_and_b32_e32 v2, 0xffffffe0, v2
	v_add_u32_e32 v180, s6, v2
	v_or_b32_e32 v2, v180, v178
	v_ashrrev_i32_e32 v3, 31, v2
	v_lshlrev_b64 v[2:3], 11, v[2:3]
	v_lshl_add_u64 v[2:3], s[42:43], 0, v[2:3]
	v_lshl_add_u64 v[2:3], v[2:3], 0, s[30:31]
	v_lshl_add_u64 v[2:3], v[2:3], 0, v[52:53]
	v_lshl_add_u64 v[6:7], v[2:3], 0, v[50:51]
	s_mov_b32 s6, 0x14610000
	v_add_co_u32_e32 v4, vcc, s6, v6
	s_mov_b32 s6, 0x14618000
	s_nop 0
	v_addc_co_u32_e32 v5, vcc, 0, v7, vcc
	v_lshl_add_u64 v[2:3], v[6:7], 0, s[10:11]
	v_add_co_u32_e32 v6, vcc, s6, v6
	s_add_u32 s6, s42, s47
	s_addc_u32 s10, s43, s46
	s_add_u32 s50, s6, s30
	s_addc_u32 s51, s10, 0
	s_lshl_b32 s6, s27, 10
	s_or_b32 s6, s49, s6
	s_mul_hi_i32 s11, s6, 0x2200
	s_mulk_i32 s6, 0x2200
	s_add_u32 s10, s42, s6
	s_addc_u32 s11, s43, s11
	s_add_u32 s14, s10, 0xe010000
	s_addc_u32 s15, s11, 0
	v_lshl_add_u64 v[18:19], s[50:51], 0, v[56:57]
	v_lshl_add_u64 v[42:43], v[18:19], 0, v[122:123]
	v_mov_b64_e32 v[18:19], s[14:15]
	v_mad_i64_i32 v[18:19], s[14:15], v54, s18, v[18:19]
	v_lshl_add_u64 v[46:47], v[18:19], 0, v[122:123]
	v_lshlrev_b32_e32 v18, 2, v54
	v_lshrrev_b32_e32 v19, 1, v54
	v_addc_co_u32_e32 v7, vcc, 0, v7, vcc
	v_and_b32_e32 v18, 16, v18
	v_and_b32_e32 v19, 12, v19
	s_mov_b32 s14, 0x16810000
	v_or3_b32 v51, v20, v18, v19
	v_add_co_u32_e32 v18, vcc, s14, v42
	s_mov_b32 s14, 0x16820000
	s_nop 0
	v_addc_co_u32_e32 v19, vcc, 0, v43, vcc
	v_add_co_u32_e32 v26, vcc, s14, v42
	s_mov_b32 s14, 0x44000
	s_nop 0
	v_addc_co_u32_e32 v27, vcc, 0, v43, vcc
	v_add_co_u32_e32 v30, vcc, s14, v46
	s_mov_b32 s14, 0x16830000
	s_nop 0
	v_addc_co_u32_e32 v31, vcc, 0, v47, vcc
	v_add_co_u32_e32 v34, vcc, s14, v42
	global_load_dwordx4 v[10:13], v[4:5], off
	s_nop 0
	global_load_dwordx4 v[2:5], v[2:3], off offset:64
	s_nop 0
	global_load_dwordx4 v[14:17], v[6:7], off
	s_nop 0
	global_load_dwordx4 v[6:9], v[6:7], off offset:64
	s_nop 0
	global_load_dwordx4 v[18:21], v[18:19], off
	s_nop 0
	global_load_dwordx4 v[22:25], v[46:47], off
	v_addc_co_u32_e32 v35, vcc, 0, v43, vcc
	s_mov_b32 s14, 0x88000
	v_add_co_u32_e32 v38, vcc, s14, v46
	global_load_dwordx4 v[26:29], v[26:27], off
	s_nop 0
	v_addc_co_u32_e32 v39, vcc, 0, v47, vcc
	s_mov_b32 s14, 0x16840000
	global_load_dwordx4 v[30:33], v[30:31], off
	v_add_co_u32_e32 v42, vcc, s14, v42
	global_load_dwordx4 v[34:37], v[34:35], off
	s_nop 0
	v_addc_co_u32_e32 v43, vcc, 0, v43, vcc
	s_mov_b32 s14, 0xcc000
	global_load_dwordx4 v[38:41], v[38:39], off
	v_add_co_u32_e32 v46, vcc, s14, v46
	global_load_dwordx4 v[42:45], v[42:43], off
	s_nop 0
	v_addc_co_u32_e32 v47, vcc, 0, v47, vcc
	global_load_dwordx4 v[46:49], v[46:47], off
	s_movk_i32 s6, 0x110
	v_mul_lo_u32 v53, v54, s6
	v_mad_u64_u32 v[124:125], s[14:15], v51, s6, v[122:123]
	s_mov_b32 s6, 0x11000
	v_add3_u32 v125, v53, v122, s6
	v_add_u32_e32 v51, 0, v124
	v_add_u32_e32 v53, 0, v125
	s_add_i32 s6, 0, 0x11000
	ds_bpermute_b32 v135, v173, v134
	s_mov_b32 s30, 0xe0dc000
	s_mov_b64 s[50:51], 0x40000
	s_waitcnt vmcnt(7)
	ds_write_b128 v51, v[18:21]
	s_waitcnt vmcnt(6)
	ds_write_b128 v53, v[22:25]
	s_waitcnt vmcnt(5)
	ds_write_b128 v51, v[26:29] offset:8704
	s_waitcnt vmcnt(4)
	ds_write_b128 v53, v[30:33] offset:8704
	s_waitcnt vmcnt(3)
	ds_write_b128 v51, v[34:37] offset:17408
	s_waitcnt vmcnt(2)
	ds_write_b128 v53, v[38:41] offset:17408
	s_waitcnt vmcnt(1)
	ds_write_b128 v51, v[42:45] offset:26112
	s_waitcnt vmcnt(0)
	ds_write_b128 v53, v[46:49] offset:26112
	v_mul_u32_u24_e32 v19, 0x110, v178
	v_add3_u32 v183, s6, v50, v19
	s_lshl_b32 s6, s26, 3
	s_and_b32 s6, s6, 0x700
	s_add_u32 s6, s42, s6
	v_add_u32_e32 v18, 0, v52
	s_addc_u32 s15, s43, 0
	v_add3_u32 v137, v18, v50, v19
	s_add_u32 s14, s6, s47
	v_mov_b64_e32 v[18:19], s[10:11]
	s_addc_u32 s15, s15, s46
	v_mad_i64_i32 v[128:129], s[10:11], v54, s18, v[18:19]
	v_mov_b32_e32 v18, 0
	v_lshl_add_u64 v[126:127], s[14:15], 0, v[56:57]
	v_mov_b32_e32 v19, v18
	v_mov_b32_e32 v20, v18
	v_mov_b32_e32 v21, v18
	v_mov_b32_e32 v22, v18
	v_mov_b32_e32 v23, v18
	v_mov_b32_e32 v24, v18
	v_mov_b32_e32 v25, v18
	v_mov_b32_e32 v26, v18
	v_mov_b32_e32 v27, v18
	v_mov_b32_e32 v28, v18
	v_mov_b32_e32 v29, v18
	v_mov_b32_e32 v38, v18
	v_mov_b32_e32 v39, v18
	v_mov_b32_e32 v40, v18
	v_mov_b32_e32 v41, v18
	v_mov_b32_e32 v46, v18
	v_mov_b32_e32 v47, v18
	v_mov_b32_e32 v48, v18
	v_mov_b32_e32 v49, v18
	v_mov_b32_e32 v54, v18
	v_mov_b32_e32 v55, v18
	v_mov_b32_e32 v56, v18
	v_mov_b32_e32 v57, v18
	v_mov_b32_e32 v62, v18
	v_mov_b32_e32 v63, v18
	v_mov_b32_e32 v64, v18
	v_mov_b32_e32 v65, v18
	v_mov_b32_e32 v74, v18
	v_mov_b32_e32 v75, v18
	v_mov_b32_e32 v76, v18
	v_mov_b32_e32 v77, v18
	v_mov_b32_e32 v30, v18
	v_mov_b32_e32 v31, v18
	v_mov_b32_e32 v32, v18
	v_mov_b32_e32 v33, v18
	v_mov_b32_e32 v34, v18
	v_mov_b32_e32 v35, v18
	v_mov_b32_e32 v36, v18
	v_mov_b32_e32 v37, v18
	v_mov_b32_e32 v42, v18
	v_mov_b32_e32 v43, v18
	v_mov_b32_e32 v44, v18
	v_mov_b32_e32 v45, v18
	v_mov_b32_e32 v50, v18
	v_mov_b32_e32 v51, v18
	v_mov_b32_e32 v52, v18
	v_mov_b32_e32 v53, v18
	v_mov_b32_e32 v58, v18
	v_mov_b32_e32 v59, v18
	v_mov_b32_e32 v60, v18
	v_mov_b32_e32 v61, v18
	v_mov_b32_e32 v66, v18
	v_mov_b32_e32 v67, v18
	v_mov_b32_e32 v68, v18
	v_mov_b32_e32 v69, v18
	v_mov_b32_e32 v70, v18
	v_mov_b32_e32 v71, v18
	v_mov_b32_e32 v72, v18
	v_mov_b32_e32 v73, v18
	v_mov_b32_e32 v78, v18
	v_mov_b32_e32 v79, v18
	v_mov_b32_e32 v80, v18
	v_mov_b32_e32 v81, v18
	v_mov_b32_e32 v118, v18
	v_mov_b32_e32 v119, v18
	s_mov_b32 s11, 0xe054000
	s_mov_b32 s14, 0x16870000
	s_mov_b32 s15, 0xe098000
	s_mov_b32 s18, 0x16880000
	s_waitcnt lgkmcnt(0)
	s_barrier
